# v75 without the per-item s_sleep skew of waves 4-7 in the MLA key loop (LDS progress flags kept)
# speedup vs baseline: 1.0089x; 1.0074x over previous
; DI void phase_attn_mla(const Params& P, bf16_t* og, unsigned char* smem, int L, int G) {
;     ...
;     for (int j = 0; j <= jhi; ++j) {
;       const int key0 = j * 64, cb = j & 1;
;       __syncthreads();
;       if (j < jhi) kv96x8_store(R, sK + (cb ^ 1) * KVB96, sVt + (cb ^ 1) * KVB96, tid);
;       if (j + 1 < jhi) kv96x8_fetch(R, knb, krb, vb, key0 + 128, tid);
;       __builtin_amdgcn_sched_barrier(0);
.LBB0_779:
	s_and_b32 s40, s26, 1
	s_add_i32 s98, s26, 1
	v_mov_b32_e32 v254, s98
	s_cmp_eq_u32 s26, 0
	s_cbranch_scc0 .Lmy_mla_spin
	s_waitcnt lgkmcnt(0)
	s_barrier
	s_branch .Lmy_mla_go
